# P0 cache_conv: batched fast path for grid=256 (8 x 16-B loads in flight per thread, constant strides)
# baseline (speedup 1.0000x reference)
.LBB0_38:
	s_ashr_i32 s3, s2, 31
	s_lshl_b64 s[4:5], s[2:3], 9
	v_mov_b32_e32 v195, 0
	v_lshl_add_u64 v[2:3], s[4:5], 0, v[194:195]
	s_mov_b64 s[4:5], 0x1fffff
	v_cmp_lt_u64_e32 vcc, s[4:5], v[2:3]
	s_ashr_i32 s23, s22, 31
	s_and_saveexec_b64 s[4:5], vcc
	s_xor_b64 s[4:5], exec, s[4:5]
	s_or_saveexec_b64 s[6:7], s[4:5]
	s_lshl_b64 s[4:5], s[22:23], 9
	v_lshlrev_b32_e32 v4, 5, v194
	v_lshlrev_b32_e32 v6, 3, v194
	s_xor_b64 exec, exec, s[6:7]
	s_cbranch_execz .LBB0_44
	s_add_u32 s12, s28, 0x11c00000
	v_mov_b32_e32 v13, 0
	s_addc_u32 s13, s29, 0
	s_lshl_b64 s[8:9], s[2:3], 14
	v_mov_b32_e32 v5, v13
	v_lshl_add_u64 v[10:11], s[8:9], 0, v[4:5]
	s_lshl_b64 s[10:11], s[2:3], 12
	v_mov_b32_e32 v7, v13
	v_or_b32_e32 v10, 16, v10
	v_lshl_add_u64 v[8:9], s[10:11], 0, v[6:7]
	v_lshl_add_u64 v[14:15], s[56:57], 0, v[10:11]
	s_lshl_b64 s[8:9], s[22:23], 14
	s_lshl_b64 s[10:11], s[22:23], 12
	s_mov_b64 s[14:15], 0
	s_movk_i32 s18, 0x4000
	s_mov_b64 s[16:17], 0x1fffff
	v_mov_b64_e32 v[16:17], v[8:9]
	v_mov_b64_e32 v[18:19], v[2:3]
	s_cmpk_lg_i32 s22, 0x100
	s_cbranch_scc1 .LBB0_40
	v_lshrrev_b32_e32 v5, 20, v16
	v_bfe_u32 v7, v16, 10, 10
	v_mul_u32_u24_e32 v5, 0x420, v5
	v_add3_u32 v12, v5, v7, s18
	v_and_b32_e32 v1, 0x3f8, v16
	v_lshlrev_b64 v[28:29], 11, v[12:13]
	v_lshlrev_b32_e32 v12, 1, v1
	v_lshl_add_u64 v[28:29], s[12:13], 0, v[28:29]
	v_lshl_add_u64 v[134:135], v[28:29], 0, v[12:13]
	v_mov_b64_e32 v[132:133], v[14:15]
	global_load_dwordx4 v[100:103], v[132:133], off offset:-16
	global_load_dwordx4 v[104:107], v[132:133], off
	v_lshl_add_u64 v[132:133], v[132:133], 0, s[8:9]
	global_load_dwordx4 v[108:111], v[132:133], off offset:-16
	global_load_dwordx4 v[112:115], v[132:133], off
	v_lshl_add_u64 v[132:133], v[132:133], 0, s[8:9]
	global_load_dwordx4 v[116:119], v[132:133], off offset:-16
	global_load_dwordx4 v[120:123], v[132:133], off
	v_lshl_add_u64 v[132:133], v[132:133], 0, s[8:9]
	global_load_dwordx4 v[124:127], v[132:133], off offset:-16
	global_load_dwordx4 v[128:131], v[132:133], off
	v_lshl_add_u64 v[132:133], v[132:133], 0, s[8:9]
	s_waitcnt vmcnt(6)
	v_cvt_pk_bf16_f32 v100, v100, v101
	v_cvt_pk_bf16_f32 v101, v102, v103
	v_cvt_pk_bf16_f32 v102, v104, v105
	v_cvt_pk_bf16_f32 v103, v106, v107
	global_store_dwordx4 v[134:135], v[100:103], off
	v_add_co_u32_e32 v134, vcc, 0x210000, v134
	s_nop 1
	v_addc_co_u32_e32 v135, vcc, 0, v135, vcc
	s_waitcnt vmcnt(5)
	v_cvt_pk_bf16_f32 v108, v108, v109
	v_cvt_pk_bf16_f32 v109, v110, v111
	v_cvt_pk_bf16_f32 v110, v112, v113
	v_cvt_pk_bf16_f32 v111, v114, v115
	global_store_dwordx4 v[134:135], v[108:111], off
	v_add_co_u32_e32 v134, vcc, 0x210000, v134
	s_nop 1
	v_addc_co_u32_e32 v135, vcc, 0, v135, vcc
	s_waitcnt vmcnt(4)
	v_cvt_pk_bf16_f32 v116, v116, v117
	v_cvt_pk_bf16_f32 v117, v118, v119
	v_cvt_pk_bf16_f32 v118, v120, v121
	v_cvt_pk_bf16_f32 v119, v122, v123
	global_store_dwordx4 v[134:135], v[116:119], off
	v_add_co_u32_e32 v134, vcc, 0x210000, v134
	s_nop 1
	v_addc_co_u32_e32 v135, vcc, 0, v135, vcc
	s_waitcnt vmcnt(3)
	v_cvt_pk_bf16_f32 v124, v124, v125
	v_cvt_pk_bf16_f32 v125, v126, v127
	v_cvt_pk_bf16_f32 v126, v128, v129
	v_cvt_pk_bf16_f32 v127, v130, v131
	global_store_dwordx4 v[134:135], v[124:127], off
	v_add_co_u32_e32 v134, vcc, 0x210000, v134
	s_nop 1
	v_addc_co_u32_e32 v135, vcc, 0, v135, vcc
	global_load_dwordx4 v[100:103], v[132:133], off offset:-16
	global_load_dwordx4 v[104:107], v[132:133], off
	v_lshl_add_u64 v[132:133], v[132:133], 0, s[8:9]
	global_load_dwordx4 v[108:111], v[132:133], off offset:-16
	global_load_dwordx4 v[112:115], v[132:133], off
	v_lshl_add_u64 v[132:133], v[132:133], 0, s[8:9]
	global_load_dwordx4 v[116:119], v[132:133], off offset:-16
	global_load_dwordx4 v[120:123], v[132:133], off
	v_lshl_add_u64 v[132:133], v[132:133], 0, s[8:9]
	global_load_dwordx4 v[124:127], v[132:133], off offset:-16
	global_load_dwordx4 v[128:131], v[132:133], off
	v_lshl_add_u64 v[132:133], v[132:133], 0, s[8:9]
	s_waitcnt vmcnt(6)
	v_cvt_pk_bf16_f32 v100, v100, v101
	v_cvt_pk_bf16_f32 v101, v102, v103
	v_cvt_pk_bf16_f32 v102, v104, v105
	v_cvt_pk_bf16_f32 v103, v106, v107
	global_store_dwordx4 v[134:135], v[100:103], off
	v_add_co_u32_e32 v134, vcc, 0x210000, v134
	s_nop 1
	v_addc_co_u32_e32 v135, vcc, 0, v135, vcc
	s_waitcnt vmcnt(5)
	v_cvt_pk_bf16_f32 v108, v108, v109
	v_cvt_pk_bf16_f32 v109, v110, v111
	v_cvt_pk_bf16_f32 v110, v112, v113
	v_cvt_pk_bf16_f32 v111, v114, v115
	global_store_dwordx4 v[134:135], v[108:111], off
	v_add_co_u32_e32 v134, vcc, 0x210000, v134
	s_nop 1
	v_addc_co_u32_e32 v135, vcc, 0, v135, vcc
	s_waitcnt vmcnt(4)
	v_cvt_pk_bf16_f32 v116, v116, v117
	v_cvt_pk_bf16_f32 v117, v118, v119
	v_cvt_pk_bf16_f32 v118, v120, v121
	v_cvt_pk_bf16_f32 v119, v122, v123
	global_store_dwordx4 v[134:135], v[116:119], off
	v_add_co_u32_e32 v134, vcc, 0x210000, v134
	s_nop 1
	v_addc_co_u32_e32 v135, vcc, 0, v135, vcc
	s_waitcnt vmcnt(3)
	v_cvt_pk_bf16_f32 v124, v124, v125
	v_cvt_pk_bf16_f32 v125, v126, v127
	v_cvt_pk_bf16_f32 v126, v128, v129
	v_cvt_pk_bf16_f32 v127, v130, v131
	global_store_dwordx4 v[134:135], v[124:127], off
	v_add_co_u32_e32 v134, vcc, 0x210000, v134
	s_nop 1
	v_addc_co_u32_e32 v135, vcc, 0, v135, vcc
	global_load_dwordx4 v[100:103], v[132:133], off offset:-16
	global_load_dwordx4 v[104:107], v[132:133], off
	v_lshl_add_u64 v[132:133], v[132:133], 0, s[8:9]
	global_load_dwordx4 v[108:111], v[132:133], off offset:-16
	global_load_dwordx4 v[112:115], v[132:133], off
	v_lshl_add_u64 v[132:133], v[132:133], 0, s[8:9]
	global_load_dwordx4 v[116:119], v[132:133], off offset:-16
	global_load_dwordx4 v[120:123], v[132:133], off
	v_lshl_add_u64 v[132:133], v[132:133], 0, s[8:9]
	global_load_dwordx4 v[124:127], v[132:133], off offset:-16
	global_load_dwordx4 v[128:131], v[132:133], off
	v_lshl_add_u64 v[132:133], v[132:133], 0, s[8:9]
	s_waitcnt vmcnt(6)
	v_cvt_pk_bf16_f32 v100, v100, v101
	v_cvt_pk_bf16_f32 v101, v102, v103
	v_cvt_pk_bf16_f32 v102, v104, v105
	v_cvt_pk_bf16_f32 v103, v106, v107
	global_store_dwordx4 v[134:135], v[100:103], off
	v_add_co_u32_e32 v134, vcc, 0x210000, v134
	s_nop 1
	v_addc_co_u32_e32 v135, vcc, 0, v135, vcc
	s_waitcnt vmcnt(5)
	v_cvt_pk_bf16_f32 v108, v108, v109
	v_cvt_pk_bf16_f32 v109, v110, v111
	v_cvt_pk_bf16_f32 v110, v112, v113
	v_cvt_pk_bf16_f32 v111, v114, v115
	global_store_dwordx4 v[134:135], v[108:111], off
	v_add_co_u32_e32 v134, vcc, 0x210000, v134
	s_nop 1
	v_addc_co_u32_e32 v135, vcc, 0, v135, vcc
	s_waitcnt vmcnt(4)
	v_cvt_pk_bf16_f32 v116, v116, v117
	v_cvt_pk_bf16_f32 v117, v118, v119
	v_cvt_pk_bf16_f32 v118, v120, v121
	v_cvt_pk_bf16_f32 v119, v122, v123
	global_store_dwordx4 v[134:135], v[116:119], off
	v_add_co_u32_e32 v134, vcc, 0x210000, v134
	s_nop 1
	v_addc_co_u32_e32 v135, vcc, 0, v135, vcc
	s_waitcnt vmcnt(3)
	v_cvt_pk_bf16_f32 v124, v124, v125
	v_cvt_pk_bf16_f32 v125, v126, v127
	v_cvt_pk_bf16_f32 v126, v128, v129
	v_cvt_pk_bf16_f32 v127, v130, v131
	global_store_dwordx4 v[134:135], v[124:127], off
	v_add_co_u32_e32 v134, vcc, 0x210000, v134
	s_nop 1
	v_addc_co_u32_e32 v135, vcc, 0, v135, vcc
	global_load_dwordx4 v[100:103], v[132:133], off offset:-16
	global_load_dwordx4 v[104:107], v[132:133], off
	v_lshl_add_u64 v[132:133], v[132:133], 0, s[8:9]
	global_load_dwordx4 v[108:111], v[132:133], off offset:-16
	global_load_dwordx4 v[112:115], v[132:133], off
	v_lshl_add_u64 v[132:133], v[132:133], 0, s[8:9]
	global_load_dwordx4 v[116:119], v[132:133], off offset:-16
	global_load_dwordx4 v[120:123], v[132:133], off
	v_lshl_add_u64 v[132:133], v[132:133], 0, s[8:9]
	global_load_dwordx4 v[124:127], v[132:133], off offset:-16
	global_load_dwordx4 v[128:131], v[132:133], off
	v_lshl_add_u64 v[132:133], v[132:133], 0, s[8:9]
	s_waitcnt vmcnt(6)
	v_cvt_pk_bf16_f32 v100, v100, v101
	v_cvt_pk_bf16_f32 v101, v102, v103
	v_cvt_pk_bf16_f32 v102, v104, v105
	v_cvt_pk_bf16_f32 v103, v106, v107
	global_store_dwordx4 v[134:135], v[100:103], off
	v_add_co_u32_e32 v134, vcc, 0x210000, v134
	s_nop 1
	v_addc_co_u32_e32 v135, vcc, 0, v135, vcc
	s_waitcnt vmcnt(5)
	v_cvt_pk_bf16_f32 v108, v108, v109
	v_cvt_pk_bf16_f32 v109, v110, v111
	v_cvt_pk_bf16_f32 v110, v112, v113
	v_cvt_pk_bf16_f32 v111, v114, v115
	global_store_dwordx4 v[134:135], v[108:111], off
	v_add_co_u32_e32 v134, vcc, 0x210000, v134
	s_nop 1
	v_addc_co_u32_e32 v135, vcc, 0, v135, vcc
	s_waitcnt vmcnt(4)
	v_cvt_pk_bf16_f32 v116, v116, v117
	v_cvt_pk_bf16_f32 v117, v118, v119
	v_cvt_pk_bf16_f32 v118, v120, v121
	v_cvt_pk_bf16_f32 v119, v122, v123
	global_store_dwordx4 v[134:135], v[116:119], off
	v_add_co_u32_e32 v134, vcc, 0x210000, v134
	s_nop 1
	v_addc_co_u32_e32 v135, vcc, 0, v135, vcc
	s_waitcnt vmcnt(3)
	v_cvt_pk_bf16_f32 v124, v124, v125
	v_cvt_pk_bf16_f32 v125, v126, v127
	v_cvt_pk_bf16_f32 v126, v128, v129
	v_cvt_pk_bf16_f32 v127, v130, v131
	global_store_dwordx4 v[134:135], v[124:127], off
	v_add_co_u32_e32 v134, vcc, 0x210000, v134
	s_nop 1
	v_addc_co_u32_e32 v135, vcc, 0, v135, vcc
	s_branch .Lcc_a_done

.Lcc_a_done:
	s_or_b64 exec, exec, s[14:15]
	s_add_u32 s12, s28, 0x15d00000
	s_addc_u32 s13, s29, 0
	v_lshl_add_u64 v[10:11], s[58:59], 0, v[10:11]
	s_mov_b64 s[14:15], 0
	s_movk_i32 s18, 0x4000
	v_mov_b32_e32 v13, 0
	s_mov_b64 s[16:17], 0x1fffff
	v_mov_b64_e32 v[14:15], v[2:3]
	s_cmpk_lg_i32 s22, 0x100
	s_cbranch_scc1 .LBB0_42
	v_lshrrev_b32_e32 v5, 20, v8
	v_bfe_u32 v7, v8, 10, 10
	v_mul_u32_u24_e32 v5, 0x420, v5
	v_add3_u32 v12, v5, v7, s18
	v_and_b32_e32 v1, 0x3f8, v8
	v_lshlrev_b64 v[28:29], 11, v[12:13]
	v_lshlrev_b32_e32 v12, 1, v1
	v_lshl_add_u64 v[28:29], s[12:13], 0, v[28:29]
	v_lshl_add_u64 v[134:135], v[28:29], 0, v[12:13]
	v_mov_b64_e32 v[132:133], v[10:11]
	global_load_dwordx4 v[100:103], v[132:133], off offset:-16
	global_load_dwordx4 v[104:107], v[132:133], off
	v_lshl_add_u64 v[132:133], v[132:133], 0, s[8:9]
	global_load_dwordx4 v[108:111], v[132:133], off offset:-16
	global_load_dwordx4 v[112:115], v[132:133], off
	v_lshl_add_u64 v[132:133], v[132:133], 0, s[8:9]
	global_load_dwordx4 v[116:119], v[132:133], off offset:-16
	global_load_dwordx4 v[120:123], v[132:133], off
	v_lshl_add_u64 v[132:133], v[132:133], 0, s[8:9]
	global_load_dwordx4 v[124:127], v[132:133], off offset:-16
	global_load_dwordx4 v[128:131], v[132:133], off
	v_lshl_add_u64 v[132:133], v[132:133], 0, s[8:9]
	s_waitcnt vmcnt(6)
	v_cvt_pk_bf16_f32 v100, v100, v101
	v_cvt_pk_bf16_f32 v101, v102, v103
	v_cvt_pk_bf16_f32 v102, v104, v105
	v_cvt_pk_bf16_f32 v103, v106, v107
	global_store_dwordx4 v[134:135], v[100:103], off
	v_add_co_u32_e32 v134, vcc, 0x210000, v134
	s_nop 1
	v_addc_co_u32_e32 v135, vcc, 0, v135, vcc
	s_waitcnt vmcnt(5)
	v_cvt_pk_bf16_f32 v108, v108, v109
	v_cvt_pk_bf16_f32 v109, v110, v111
	v_cvt_pk_bf16_f32 v110, v112, v113
	v_cvt_pk_bf16_f32 v111, v114, v115
	global_store_dwordx4 v[134:135], v[108:111], off
	v_add_co_u32_e32 v134, vcc, 0x210000, v134
	s_nop 1
	v_addc_co_u32_e32 v135, vcc, 0, v135, vcc
	s_waitcnt vmcnt(4)
	v_cvt_pk_bf16_f32 v116, v116, v117
	v_cvt_pk_bf16_f32 v117, v118, v119
	v_cvt_pk_bf16_f32 v118, v120, v121
	v_cvt_pk_bf16_f32 v119, v122, v123
	global_store_dwordx4 v[134:135], v[116:119], off
	v_add_co_u32_e32 v134, vcc, 0x210000, v134
	s_nop 1
	v_addc_co_u32_e32 v135, vcc, 0, v135, vcc
	s_waitcnt vmcnt(3)
	v_cvt_pk_bf16_f32 v124, v124, v125
	v_cvt_pk_bf16_f32 v125, v126, v127
	v_cvt_pk_bf16_f32 v126, v128, v129
	v_cvt_pk_bf16_f32 v127, v130, v131
	global_store_dwordx4 v[134:135], v[124:127], off
	v_add_co_u32_e32 v134, vcc, 0x210000, v134
	s_nop 1
	v_addc_co_u32_e32 v135, vcc, 0, v135, vcc
	global_load_dwordx4 v[100:103], v[132:133], off offset:-16
	global_load_dwordx4 v[104:107], v[132:133], off
	v_lshl_add_u64 v[132:133], v[132:133], 0, s[8:9]
	global_load_dwordx4 v[108:111], v[132:133], off offset:-16
	global_load_dwordx4 v[112:115], v[132:133], off
	v_lshl_add_u64 v[132:133], v[132:133], 0, s[8:9]
	global_load_dwordx4 v[116:119], v[132:133], off offset:-16
	global_load_dwordx4 v[120:123], v[132:133], off
	v_lshl_add_u64 v[132:133], v[132:133], 0, s[8:9]
	global_load_dwordx4 v[124:127], v[132:133], off offset:-16
	global_load_dwordx4 v[128:131], v[132:133], off
	v_lshl_add_u64 v[132:133], v[132:133], 0, s[8:9]
	s_waitcnt vmcnt(6)
	v_cvt_pk_bf16_f32 v100, v100, v101
	v_cvt_pk_bf16_f32 v101, v102, v103
	v_cvt_pk_bf16_f32 v102, v104, v105
	v_cvt_pk_bf16_f32 v103, v106, v107
	global_store_dwordx4 v[134:135], v[100:103], off
	v_add_co_u32_e32 v134, vcc, 0x210000, v134
	s_nop 1
	v_addc_co_u32_e32 v135, vcc, 0, v135, vcc
	s_waitcnt vmcnt(5)
	v_cvt_pk_bf16_f32 v108, v108, v109
	v_cvt_pk_bf16_f32 v109, v110, v111
	v_cvt_pk_bf16_f32 v110, v112, v113
	v_cvt_pk_bf16_f32 v111, v114, v115
	global_store_dwordx4 v[134:135], v[108:111], off
	v_add_co_u32_e32 v134, vcc, 0x210000, v134
	s_nop 1
	v_addc_co_u32_e32 v135, vcc, 0, v135, vcc
	s_waitcnt vmcnt(4)
	v_cvt_pk_bf16_f32 v116, v116, v117
	v_cvt_pk_bf16_f32 v117, v118, v119
	v_cvt_pk_bf16_f32 v118, v120, v121
	v_cvt_pk_bf16_f32 v119, v122, v123
	global_store_dwordx4 v[134:135], v[116:119], off
	v_add_co_u32_e32 v134, vcc, 0x210000, v134
	s_nop 1
	v_addc_co_u32_e32 v135, vcc, 0, v135, vcc
	s_waitcnt vmcnt(3)
	v_cvt_pk_bf16_f32 v124, v124, v125
	v_cvt_pk_bf16_f32 v125, v126, v127
	v_cvt_pk_bf16_f32 v126, v128, v129
	v_cvt_pk_bf16_f32 v127, v130, v131
	global_store_dwordx4 v[134:135], v[124:127], off
	v_add_co_u32_e32 v134, vcc, 0x210000, v134
	s_nop 1
	v_addc_co_u32_e32 v135, vcc, 0, v135, vcc
	global_load_dwordx4 v[100:103], v[132:133], off offset:-16
	global_load_dwordx4 v[104:107], v[132:133], off
	v_lshl_add_u64 v[132:133], v[132:133], 0, s[8:9]
	global_load_dwordx4 v[108:111], v[132:133], off offset:-16
	global_load_dwordx4 v[112:115], v[132:133], off
	v_lshl_add_u64 v[132:133], v[132:133], 0, s[8:9]
	global_load_dwordx4 v[116:119], v[132:133], off offset:-16
	global_load_dwordx4 v[120:123], v[132:133], off
	v_lshl_add_u64 v[132:133], v[132:133], 0, s[8:9]
	global_load_dwordx4 v[124:127], v[132:133], off offset:-16
	global_load_dwordx4 v[128:131], v[132:133], off
	v_lshl_add_u64 v[132:133], v[132:133], 0, s[8:9]
	s_waitcnt vmcnt(6)
	v_cvt_pk_bf16_f32 v100, v100, v101
	v_cvt_pk_bf16_f32 v101, v102, v103
	v_cvt_pk_bf16_f32 v102, v104, v105
	v_cvt_pk_bf16_f32 v103, v106, v107
	global_store_dwordx4 v[134:135], v[100:103], off
	v_add_co_u32_e32 v134, vcc, 0x210000, v134
	s_nop 1
	v_addc_co_u32_e32 v135, vcc, 0, v135, vcc
	s_waitcnt vmcnt(5)
	v_cvt_pk_bf16_f32 v108, v108, v109
	v_cvt_pk_bf16_f32 v109, v110, v111
	v_cvt_pk_bf16_f32 v110, v112, v113
	v_cvt_pk_bf16_f32 v111, v114, v115
	global_store_dwordx4 v[134:135], v[108:111], off
	v_add_co_u32_e32 v134, vcc, 0x210000, v134
	s_nop 1
	v_addc_co_u32_e32 v135, vcc, 0, v135, vcc
	s_waitcnt vmcnt(4)
	v_cvt_pk_bf16_f32 v116, v116, v117
	v_cvt_pk_bf16_f32 v117, v118, v119
	v_cvt_pk_bf16_f32 v118, v120, v121
	v_cvt_pk_bf16_f32 v119, v122, v123
	global_store_dwordx4 v[134:135], v[116:119], off
	v_add_co_u32_e32 v134, vcc, 0x210000, v134
	s_nop 1
	v_addc_co_u32_e32 v135, vcc, 0, v135, vcc
	s_waitcnt vmcnt(3)
	v_cvt_pk_bf16_f32 v124, v124, v125
	v_cvt_pk_bf16_f32 v125, v126, v127
	v_cvt_pk_bf16_f32 v126, v128, v129
	v_cvt_pk_bf16_f32 v127, v130, v131
	global_store_dwordx4 v[134:135], v[124:127], off
	v_add_co_u32_e32 v134, vcc, 0x210000, v134
	s_nop 1
	v_addc_co_u32_e32 v135, vcc, 0, v135, vcc
	global_load_dwordx4 v[100:103], v[132:133], off offset:-16
	global_load_dwordx4 v[104:107], v[132:133], off
	v_lshl_add_u64 v[132:133], v[132:133], 0, s[8:9]
	global_load_dwordx4 v[108:111], v[132:133], off offset:-16
	global_load_dwordx4 v[112:115], v[132:133], off
	v_lshl_add_u64 v[132:133], v[132:133], 0, s[8:9]
	global_load_dwordx4 v[116:119], v[132:133], off offset:-16
	global_load_dwordx4 v[120:123], v[132:133], off
	v_lshl_add_u64 v[132:133], v[132:133], 0, s[8:9]
	global_load_dwordx4 v[124:127], v[132:133], off offset:-16
	global_load_dwordx4 v[128:131], v[132:133], off
	v_lshl_add_u64 v[132:133], v[132:133], 0, s[8:9]
	s_waitcnt vmcnt(6)
	v_cvt_pk_bf16_f32 v100, v100, v101
	v_cvt_pk_bf16_f32 v101, v102, v103
	v_cvt_pk_bf16_f32 v102, v104, v105
	v_cvt_pk_bf16_f32 v103, v106, v107
	global_store_dwordx4 v[134:135], v[100:103], off
	v_add_co_u32_e32 v134, vcc, 0x210000, v134
	s_nop 1
	v_addc_co_u32_e32 v135, vcc, 0, v135, vcc
	s_waitcnt vmcnt(5)
	v_cvt_pk_bf16_f32 v108, v108, v109
	v_cvt_pk_bf16_f32 v109, v110, v111
	v_cvt_pk_bf16_f32 v110, v112, v113
	v_cvt_pk_bf16_f32 v111, v114, v115
	global_store_dwordx4 v[134:135], v[108:111], off
	v_add_co_u32_e32 v134, vcc, 0x210000, v134
	s_nop 1
	v_addc_co_u32_e32 v135, vcc, 0, v135, vcc
	s_waitcnt vmcnt(4)
	v_cvt_pk_bf16_f32 v116, v116, v117
	v_cvt_pk_bf16_f32 v117, v118, v119
	v_cvt_pk_bf16_f32 v118, v120, v121
	v_cvt_pk_bf16_f32 v119, v122, v123
	global_store_dwordx4 v[134:135], v[116:119], off
	v_add_co_u32_e32 v134, vcc, 0x210000, v134
	s_nop 1
	v_addc_co_u32_e32 v135, vcc, 0, v135, vcc
	s_waitcnt vmcnt(3)
	v_cvt_pk_bf16_f32 v124, v124, v125
	v_cvt_pk_bf16_f32 v125, v126, v127
	v_cvt_pk_bf16_f32 v126, v128, v129
	v_cvt_pk_bf16_f32 v127, v130, v131
	global_store_dwordx4 v[134:135], v[124:127], off
	v_add_co_u32_e32 v134, vcc, 0x210000, v134
	s_nop 1
	v_addc_co_u32_e32 v135, vcc, 0, v135, vcc
	s_branch .Lcc_b_done
.LBB0_42:
	global_load_dwordx4 v[16:19], v[10:11], off offset:-16
	global_load_dwordx4 v[20:23], v[10:11], off
	v_lshrrev_b32_e32 v5, 20, v8
	v_bfe_u32 v7, v8, 10, 10
	v_mul_u32_u24_e32 v5, 0x420, v5
	v_add3_u32 v12, v5, v7, s18
	v_and_b32_e32 v1, 0x3f8, v8
	v_lshl_add_u64 v[14:15], v[14:15], 0, s[4:5]
	v_lshlrev_b64 v[24:25], 11, v[12:13]
	v_cmp_lt_u64_e32 vcc, s[16:17], v[14:15]
	v_lshlrev_b32_e32 v12, 1, v1
	v_lshl_add_u64 v[24:25], s[12:13], 0, v[24:25]
	v_lshl_add_u64 v[10:11], v[10:11], 0, s[8:9]
	v_lshl_add_u64 v[8:9], v[8:9], 0, s[10:11]
	s_or_b64 s[14:15], vcc, s[14:15]
	v_lshl_add_u64 v[24:25], v[24:25], 0, v[12:13]
	s_waitcnt vmcnt(1)
	v_cvt_pk_bf16_f32 v16, v16, v17
	v_cvt_pk_bf16_f32 v17, v18, v19
	s_waitcnt vmcnt(0)
	v_cvt_pk_bf16_f32 v18, v20, v21
	v_cvt_pk_bf16_f32 v19, v22, v23
	global_store_dwordx4 v[24:25], v[16:19], off
	s_andn2_b64 exec, exec, s[14:15]
	s_cbranch_execnz .LBB0_42
.Lcc_b_done:
	s_or_b64 exec, exec, s[14:15]
.LBB0_44:
	s_or_b64 exec, exec, s[6:7]
	s_mov_b64 s[6:7], 0x7ffff
	v_cmp_lt_u64_e32 vcc, s[6:7], v[2:3]
	s_and_saveexec_b64 s[6:7], vcc
	s_xor_b64 s[6:7], exec, s[6:7]
	s_andn2_saveexec_b64 s[6:7], s[6:7]
	s_cbranch_execz .LBB0_50
	s_add_u32 s12, s28, 0x19e00000
	v_mov_b32_e32 v13, 0
	s_addc_u32 s13, s29, 0
	s_lshl_b64 s[8:9], s[2:3], 14
	v_mov_b32_e32 v5, v13
	v_lshl_add_u64 v[10:11], s[8:9], 0, v[4:5]
	s_lshl_b64 s[10:11], s[2:3], 12
	v_mov_b32_e32 v7, v13
	v_or_b32_e32 v10, 16, v10
	v_lshl_add_u64 v[8:9], s[10:11], 0, v[6:7]
	v_lshl_add_u64 v[14:15], s[60:61], 0, v[10:11]
	s_lshl_b64 s[8:9], s[22:23], 14
	s_lshl_b64 s[10:11], s[22:23], 12
	s_mov_b64 s[14:15], 0
	s_movk_i32 s18, 0x4000
	s_mov_b64 s[16:17], 0x7ffff
	v_mov_b64_e32 v[16:17], v[8:9]
	v_mov_b64_e32 v[18:19], v[2:3]
	s_cmpk_lg_i32 s22, 0x100
	s_cbranch_scc1 .LBB0_46
	v_lshrrev_b32_e32 v5, 18, v16
	v_bfe_u32 v7, v16, 8, 10
	v_mul_u32_u24_e32 v5, 0x420, v5
	v_add3_u32 v12, v5, v7, s18
	v_and_b32_e32 v1, 0xf8, v16
	v_lshlrev_b64 v[28:29], 9, v[12:13]
	v_lshlrev_b32_e32 v12, 1, v1
	v_lshl_add_u64 v[28:29], s[12:13], 0, v[28:29]
	v_lshl_add_u64 v[134:135], v[28:29], 0, v[12:13]
	v_mov_b64_e32 v[132:133], v[14:15]
	global_load_dwordx4 v[100:103], v[132:133], off offset:-16
	global_load_dwordx4 v[104:107], v[132:133], off
	v_lshl_add_u64 v[132:133], v[132:133], 0, s[8:9]
	global_load_dwordx4 v[108:111], v[132:133], off offset:-16
	global_load_dwordx4 v[112:115], v[132:133], off
	v_lshl_add_u64 v[132:133], v[132:133], 0, s[8:9]
	global_load_dwordx4 v[116:119], v[132:133], off offset:-16
	global_load_dwordx4 v[120:123], v[132:133], off
	v_lshl_add_u64 v[132:133], v[132:133], 0, s[8:9]
	global_load_dwordx4 v[124:127], v[132:133], off offset:-16
	global_load_dwordx4 v[128:131], v[132:133], off
	v_lshl_add_u64 v[132:133], v[132:133], 0, s[8:9]
	s_waitcnt vmcnt(6)
	v_cvt_pk_bf16_f32 v100, v100, v101
	v_cvt_pk_bf16_f32 v101, v102, v103
	v_cvt_pk_bf16_f32 v102, v104, v105
	v_cvt_pk_bf16_f32 v103, v106, v107
	global_store_dwordx4 v[134:135], v[100:103], off
	v_add_co_u32_e32 v134, vcc, 0x210000, v134
	s_nop 1
	v_addc_co_u32_e32 v135, vcc, 0, v135, vcc
	s_waitcnt vmcnt(5)
	v_cvt_pk_bf16_f32 v108, v108, v109
	v_cvt_pk_bf16_f32 v109, v110, v111
	v_cvt_pk_bf16_f32 v110, v112, v113
	v_cvt_pk_bf16_f32 v111, v114, v115
	global_store_dwordx4 v[134:135], v[108:111], off
	v_add_co_u32_e32 v134, vcc, 0x210000, v134
	s_nop 1
	v_addc_co_u32_e32 v135, vcc, 0, v135, vcc
	s_waitcnt vmcnt(4)
	v_cvt_pk_bf16_f32 v116, v116, v117
	v_cvt_pk_bf16_f32 v117, v118, v119
	v_cvt_pk_bf16_f32 v118, v120, v121
	v_cvt_pk_bf16_f32 v119, v122, v123
	global_store_dwordx4 v[134:135], v[116:119], off
	v_add_co_u32_e32 v134, vcc, 0x210000, v134
	s_nop 1
	v_addc_co_u32_e32 v135, vcc, 0, v135, vcc
	s_waitcnt vmcnt(3)
	v_cvt_pk_bf16_f32 v124, v124, v125
	v_cvt_pk_bf16_f32 v125, v126, v127
	v_cvt_pk_bf16_f32 v126, v128, v129
	v_cvt_pk_bf16_f32 v127, v130, v131
	global_store_dwordx4 v[134:135], v[124:127], off
	v_add_co_u32_e32 v134, vcc, 0x210000, v134
	s_nop 1
	v_addc_co_u32_e32 v135, vcc, 0, v135, vcc
	s_branch .Lcc_c_done

.Lcc_c_done:
	s_or_b64 exec, exec, s[14:15]
	s_add_u32 s12, s28, 0x1ae40000
	s_addc_u32 s13, s29, 0
	v_lshl_add_u64 v[10:11], s[62:63], 0, v[10:11]
	s_mov_b64 s[14:15], 0
	s_movk_i32 s18, 0x4000
	v_mov_b32_e32 v13, 0
	s_mov_b64 s[16:17], 0x7ffff
	v_mov_b64_e32 v[14:15], v[2:3]
	s_cmpk_lg_i32 s22, 0x100
	s_cbranch_scc1 .LBB0_48
	v_lshrrev_b32_e32 v5, 18, v8
	v_bfe_u32 v7, v8, 8, 10
	v_mul_u32_u24_e32 v5, 0x420, v5
	v_add3_u32 v12, v5, v7, s18
	v_and_b32_e32 v1, 0xf8, v8
	v_lshlrev_b64 v[28:29], 9, v[12:13]
	v_lshlrev_b32_e32 v12, 1, v1
	v_lshl_add_u64 v[28:29], s[12:13], 0, v[28:29]
	v_lshl_add_u64 v[134:135], v[28:29], 0, v[12:13]
	v_mov_b64_e32 v[132:133], v[10:11]
	global_load_dwordx4 v[100:103], v[132:133], off offset:-16
	global_load_dwordx4 v[104:107], v[132:133], off
	v_lshl_add_u64 v[132:133], v[132:133], 0, s[8:9]
	global_load_dwordx4 v[108:111], v[132:133], off offset:-16
	global_load_dwordx4 v[112:115], v[132:133], off
	v_lshl_add_u64 v[132:133], v[132:133], 0, s[8:9]
	global_load_dwordx4 v[116:119], v[132:133], off offset:-16
	global_load_dwordx4 v[120:123], v[132:133], off
	v_lshl_add_u64 v[132:133], v[132:133], 0, s[8:9]
	global_load_dwordx4 v[124:127], v[132:133], off offset:-16
	global_load_dwordx4 v[128:131], v[132:133], off
	v_lshl_add_u64 v[132:133], v[132:133], 0, s[8:9]
	s_waitcnt vmcnt(6)
	v_cvt_pk_bf16_f32 v100, v100, v101
	v_cvt_pk_bf16_f32 v101, v102, v103
	v_cvt_pk_bf16_f32 v102, v104, v105
	v_cvt_pk_bf16_f32 v103, v106, v107
	global_store_dwordx4 v[134:135], v[100:103], off
	v_add_co_u32_e32 v134, vcc, 0x210000, v134
	s_nop 1
	v_addc_co_u32_e32 v135, vcc, 0, v135, vcc
	s_waitcnt vmcnt(5)
	v_cvt_pk_bf16_f32 v108, v108, v109
	v_cvt_pk_bf16_f32 v109, v110, v111
	v_cvt_pk_bf16_f32 v110, v112, v113
	v_cvt_pk_bf16_f32 v111, v114, v115
	global_store_dwordx4 v[134:135], v[108:111], off
	v_add_co_u32_e32 v134, vcc, 0x210000, v134
	s_nop 1
	v_addc_co_u32_e32 v135, vcc, 0, v135, vcc
	s_waitcnt vmcnt(4)
	v_cvt_pk_bf16_f32 v116, v116, v117
	v_cvt_pk_bf16_f32 v117, v118, v119
	v_cvt_pk_bf16_f32 v118, v120, v121
	v_cvt_pk_bf16_f32 v119, v122, v123
	global_store_dwordx4 v[134:135], v[116:119], off
	v_add_co_u32_e32 v134, vcc, 0x210000, v134
	s_nop 1
	v_addc_co_u32_e32 v135, vcc, 0, v135, vcc
	s_waitcnt vmcnt(3)
	v_cvt_pk_bf16_f32 v124, v124, v125
	v_cvt_pk_bf16_f32 v125, v126, v127
	v_cvt_pk_bf16_f32 v126, v128, v129
	v_cvt_pk_bf16_f32 v127, v130, v131
	global_store_dwordx4 v[134:135], v[124:127], off
	v_add_co_u32_e32 v134, vcc, 0x210000, v134
	s_nop 1
	v_addc_co_u32_e32 v135, vcc, 0, v135, vcc
	s_branch .Lcc_d_done
.LBB0_48:
	global_load_dwordx4 v[16:19], v[10:11], off offset:-16
	global_load_dwordx4 v[20:23], v[10:11], off
	v_lshrrev_b32_e32 v5, 18, v8
	v_bfe_u32 v7, v8, 8, 10
	v_mul_u32_u24_e32 v5, 0x420, v5
	v_add3_u32 v12, v5, v7, s18
	v_and_b32_e32 v1, 0xf8, v8
	v_lshl_add_u64 v[14:15], v[14:15], 0, s[4:5]
	v_lshlrev_b64 v[24:25], 9, v[12:13]
	v_cmp_lt_u64_e32 vcc, s[16:17], v[14:15]
	v_lshlrev_b32_e32 v12, 1, v1
	v_lshl_add_u64 v[24:25], s[12:13], 0, v[24:25]
	v_lshl_add_u64 v[10:11], v[10:11], 0, s[8:9]
	v_lshl_add_u64 v[8:9], v[8:9], 0, s[10:11]
	s_or_b64 s[14:15], vcc, s[14:15]
	v_lshl_add_u64 v[24:25], v[24:25], 0, v[12:13]
	s_waitcnt vmcnt(1)
	v_cvt_pk_bf16_f32 v16, v16, v17
	v_cvt_pk_bf16_f32 v17, v18, v19
	s_waitcnt vmcnt(0)
	v_cvt_pk_bf16_f32 v18, v20, v21
	v_cvt_pk_bf16_f32 v19, v22, v23
	global_store_dwordx4 v[24:25], v[16:19], off
	s_andn2_b64 exec, exec, s[14:15]
	s_cbranch_execnz .LBB0_48
.Lcc_d_done:
	s_or_b64 exec, exec, s[14:15]
.LBB0_50:
	s_or_b64 exec, exec, s[6:7]
	s_mov_b64 s[6:7], 0x20000
	v_cmp_gt_u64_e32 vcc, s[6:7], v[2:3]
	s_and_saveexec_b64 s[6:7], vcc
	s_cbranch_execz .LBB0_53
	s_add_u32 s8, s28, 0x1be80000
	s_addc_u32 s9, s29, 0
	s_lshl_b64 s[10:11], s[2:3], 14
	s_add_u32 s10, s64, s10
	v_mov_b32_e32 v5, 0
	s_addc_u32 s11, s65, s11
	v_lshl_add_u64 v[8:9], s[10:11], 0, v[4:5]
	s_lshl_b64 s[12:13], s[2:3], 12
	v_mov_b32_e32 v7, v5
	v_lshl_add_u64 v[8:9], v[8:9], 0, 16
	s_lshl_b64 s[10:11], s[22:23], 14
	v_lshl_add_u64 v[6:7], s[12:13], 0, v[6:7]
	s_lshl_b64 s[12:13], s[22:23], 12
	s_mov_b64 s[14:15], 0
	s_movk_i32 s3, 0x420
	s_movk_i32 s18, 0x4000
	s_mov_b64 s[16:17], 0x1ffff
